# barrier leader no longer waits for its release atomic to complete (invalidate is already done at arrival)
# baseline (speedup 1.0000x reference)
; __device__ __forceinline__ unsigned xb_add(unsigned* p, unsigned v) { return __hip_atomic_fetch_add(p, v, __ATOMIC_RELAXED, __HIP_MEMORY_SCOPE_AGENT); }
; __device__ __forceinline__ void xcd_barrier(const XcdBarrier& b) {
;     ...
;             xb_add(&bar[XB_XGEN(b.x)], 1u);
;             asm volatile("s_waitcnt vmcnt(0)" ::: "memory");
.LBB0_371:
	s_or_b64 exec, exec, s[10:11]
	s_nop 0

; __device__ __forceinline__ unsigned xb_add(unsigned* p, unsigned v) { return __hip_atomic_fetch_add(p, v, __ATOMIC_RELAXED, __HIP_MEMORY_SCOPE_AGENT); }
; __device__ __forceinline__ void xcd_barrier(const XcdBarrier& b) {
;     ...
;             xb_add(&bar[XB_XGEN(b.x)], 1u);
;             asm volatile("s_waitcnt vmcnt(0)" ::: "memory");
.LBB0_733:
	s_or_b64 exec, exec, s[12:13]
	s_nop 0

; __device__ __forceinline__ unsigned xb_add(unsigned* p, unsigned v) { return __hip_atomic_fetch_add(p, v, __ATOMIC_RELAXED, __HIP_MEMORY_SCOPE_AGENT); }
; __device__ __forceinline__ void xcd_barrier(const XcdBarrier& b) {
;     ...
;             xb_add(&bar[XB_XGEN(b.x)], 1u);
;             asm volatile("s_waitcnt vmcnt(0)" ::: "memory");
.LBB0_979:
	s_or_b64 exec, exec, s[8:9]
	s_nop 0
